# p11 + E1 epilogue: same ds_bpermute lane transpose of the bf16 output chunks (four consecutive lanes store 64 contiguous bytes)
# speedup vs baseline: 1.0072x; 1.0012x over previous
.LBB0_508:
.LBB0_510:
	v_mbcnt_lo_u32_b32 v255, -1, 0
	v_mbcnt_hi_u32_b32 v255, -1, v255
	v_lshrrev_b32_e32 v206, 2, v255
	v_and_b32_e32 v207, 3, v255
	v_and_b32_e32 v208, 15, v255
	v_lshrrev_b32_e32 v209, 4, v255
	v_sub_u32_e32 v208, v206, v208
	v_sub_u32_e32 v209, v207, v209
	v_mul_i32_i24_e32 v208, 0x1800, v208
	v_lshl_add_u32 v252, v209, 4, v208
	v_ashrrev_i32_e32 v253, 31, v252
	v_lshl_add_u32 v255, v207, 4, v206
	v_lshlrev_b32_e32 v255, 2, v255
	ds_read_b128 v[158:161], v167
	ds_read_b128 v[168:171], v167 offset:1024
	s_mul_hi_i32 s8, s2, 0x2aaaaaab
	s_lshr_b32 s9, s8, 31
	s_ashr_i32 s8, s8, 1
	s_add_i32 s15, s8, s9
	v_mov_b32_e32 v0, 0xf000000
	v_mad_i64_i32 v[152:153], s[8:9], s15, v0, v[140:141]
	s_waitcnt lgkmcnt(0)
	v_lshlrev_b32_e32 v0, 16, v158
	v_and_b32_e32 v150, 0xffff0000, v158
	v_add_f32_e32 v0, v0, v150
	v_lshlrev_b32_e32 v150, 16, v159
	v_and_b32_e32 v151, 0xffff0000, v159
	v_add_f32_e32 v150, v150, v151
	v_add_f32_e32 v0, v0, v150
	v_lshlrev_b32_e32 v150, 16, v160
	v_and_b32_e32 v151, 0xffff0000, v160
	v_add_f32_e32 v150, v150, v151
	v_lshlrev_b32_e32 v151, 16, v161
	v_and_b32_e32 v154, 0xffff0000, v161
	v_add_f32_e32 v151, v151, v154
	v_add_f32_e32 v150, v150, v151
	v_add_f32_e32 v0, v0, v150
	v_mov_b32_e32 v150, v0
	s_nop 1
	v_permlane16_swap_b32_e32 v0, v150
	v_add_f32_e32 v0, v0, v150
	v_mov_b32_e32 v150, v0
	s_nop 1
	v_permlane32_swap_b32_e32 v0, v150
	v_add_f32_e32 v0, v0, v150
	v_lshlrev_b32_e32 v150, 16, v168
	v_and_b32_e32 v151, 0xffff0000, v168
	v_add_f32_e32 v150, v150, v151
	v_lshlrev_b32_e32 v151, 16, v169
	v_and_b32_e32 v154, 0xffff0000, v169
	v_add_f32_e32 v151, v151, v154
	v_add_f32_e32 v150, v150, v151
	v_lshlrev_b32_e32 v151, 16, v170
	v_and_b32_e32 v154, 0xffff0000, v170
	v_add_f32_e32 v151, v151, v154
	v_lshlrev_b32_e32 v154, 16, v171
	v_and_b32_e32 v155, 0xffff0000, v171
	v_add_f32_e32 v154, v154, v155
	ds_read_b128 v[158:161], v167 offset:2048
	ds_read_b128 v[176:179], v167 offset:3072
	v_add_f32_e32 v151, v151, v154
	v_add_f32_e32 v150, v150, v151
	v_mov_b32_e32 v151, v150
	s_nop 1
	v_permlane16_swap_b32_e32 v150, v151
	v_add_f32_e32 v173, v150, v151
	s_waitcnt lgkmcnt(0)
	v_lshlrev_b32_e32 v150, 16, v158
	v_and_b32_e32 v151, 0xffff0000, v158
	v_add_f32_e32 v150, v150, v151
	v_lshlrev_b32_e32 v151, 16, v159
	v_and_b32_e32 v154, 0xffff0000, v159
	v_add_f32_e32 v151, v151, v154
	v_add_f32_e32 v150, v150, v151
	v_lshlrev_b32_e32 v151, 16, v160
	v_and_b32_e32 v154, 0xffff0000, v160
	v_add_f32_e32 v151, v151, v154
	v_lshlrev_b32_e32 v154, 16, v161
	v_and_b32_e32 v155, 0xffff0000, v161
	v_add_f32_e32 v154, v154, v155
	v_add_f32_e32 v151, v151, v154
	v_add_f32_e32 v150, v150, v151
	v_mov_b32_e32 v151, v150
	s_nop 1
	v_permlane16_swap_b32_e32 v150, v151
	v_add_f32_e32 v171, v150, v151
	v_lshlrev_b32_e32 v150, 16, v176
	v_and_b32_e32 v151, 0xffff0000, v176
	v_add_f32_e32 v150, v150, v151
	v_lshlrev_b32_e32 v151, 16, v177
	v_and_b32_e32 v154, 0xffff0000, v177
	v_add_f32_e32 v151, v151, v154
	v_add_f32_e32 v150, v150, v151
	v_lshlrev_b32_e32 v151, 16, v178
	v_and_b32_e32 v154, 0xffff0000, v178
	v_add_f32_e32 v151, v151, v154
	v_lshlrev_b32_e32 v154, 16, v179
	v_and_b32_e32 v155, 0xffff0000, v179
	v_add_f32_e32 v154, v154, v155
	ds_read_b128 v[158:161], v167 offset:8192
	ds_read_b128 v[176:179], v167 offset:9216
	v_add_f32_e32 v151, v151, v154
	v_add_f32_e32 v150, v150, v151
	v_mov_b32_e32 v151, v150
	s_nop 1
	v_permlane16_swap_b32_e32 v150, v151
	v_add_f32_e32 v169, v150, v151
	s_waitcnt lgkmcnt(0)
	v_lshlrev_b32_e32 v150, 16, v158
	v_and_b32_e32 v151, 0xffff0000, v158
	v_add_f32_e32 v150, v150, v151
	v_lshlrev_b32_e32 v151, 16, v159
	v_and_b32_e32 v154, 0xffff0000, v159
	v_add_f32_e32 v151, v151, v154
	v_add_f32_e32 v150, v150, v151
	v_lshlrev_b32_e32 v151, 16, v160
	v_and_b32_e32 v154, 0xffff0000, v160
	v_add_f32_e32 v151, v151, v154
	v_lshlrev_b32_e32 v154, 16, v161
	v_and_b32_e32 v155, 0xffff0000, v161
	v_add_f32_e32 v154, v154, v155
	v_add_f32_e32 v151, v151, v154
	v_add_f32_e32 v150, v150, v151
	s_mov_b64 vcc, s[10:11]
	s_cbranch_vccz .Lalign_skip_1
	s_barrier
.Lalign_skip_1:
	v_mov_b32_e32 v151, v150
	s_nop 1
	v_permlane16_swap_b32_e32 v150, v151
	v_add_f32_e32 v161, v150, v151
	v_lshlrev_b32_e32 v150, 16, v176
	v_and_b32_e32 v151, 0xffff0000, v176
	v_add_f32_e32 v150, v150, v151
	v_lshlrev_b32_e32 v151, 16, v177
	v_and_b32_e32 v154, 0xffff0000, v177
	v_add_f32_e32 v151, v151, v154
	v_add_f32_e32 v150, v150, v151
	v_lshlrev_b32_e32 v151, 16, v178
	v_and_b32_e32 v154, 0xffff0000, v178
	v_add_f32_e32 v151, v151, v154
	v_lshlrev_b32_e32 v154, 16, v179
	v_and_b32_e32 v155, 0xffff0000, v179
	v_add_f32_e32 v154, v154, v155
	ds_read_b128 v[176:179], v167 offset:10240
	ds_read_b128 v[180:183], v167 offset:11264
	v_add_f32_e32 v151, v151, v154
	v_add_f32_e32 v150, v150, v151
	v_mov_b32_e32 v151, v150
	s_nop 1
	v_permlane16_swap_b32_e32 v150, v151
	v_add_f32_e32 v159, v150, v151
	s_waitcnt lgkmcnt(0)
	v_lshlrev_b32_e32 v150, 16, v176
	v_and_b32_e32 v151, 0xffff0000, v176
	v_add_f32_e32 v150, v150, v151
	v_lshlrev_b32_e32 v151, 16, v177
	v_and_b32_e32 v154, 0xffff0000, v177
	v_add_f32_e32 v151, v151, v154
	v_add_f32_e32 v150, v150, v151
	v_lshlrev_b32_e32 v151, 16, v178
	v_and_b32_e32 v154, 0xffff0000, v178
	v_add_f32_e32 v151, v151, v154
	v_lshlrev_b32_e32 v154, 16, v179
	v_and_b32_e32 v155, 0xffff0000, v179
	v_add_f32_e32 v154, v154, v155
	v_add_f32_e32 v151, v151, v154
	v_add_f32_e32 v150, v150, v151
	v_mov_b32_e32 v151, v150
	s_nop 1
	v_permlane16_swap_b32_e32 v150, v151
	v_add_f32_e32 v157, v150, v151
	v_lshlrev_b32_e32 v150, 16, v180
	v_and_b32_e32 v151, 0xffff0000, v180
	v_add_f32_e32 v150, v150, v151
	v_lshlrev_b32_e32 v151, 16, v181
	v_and_b32_e32 v154, 0xffff0000, v181
	v_add_f32_e32 v151, v151, v154
	v_add_f32_e32 v150, v150, v151
	v_lshlrev_b32_e32 v151, 16, v182
	v_and_b32_e32 v154, 0xffff0000, v182
	v_add_f32_e32 v151, v151, v154
	v_lshlrev_b32_e32 v154, 16, v183
	v_and_b32_e32 v155, 0xffff0000, v183
	v_add_f32_e32 v154, v154, v155
	s_lshl_b32 s13, s2, 8
	s_mul_i32 s8, s15, 0xfffff400
	v_add_f32_e32 v151, v151, v154
	s_add_i32 s8, s8, s13
	v_add_f32_e32 v150, v150, v151
	v_fmamk_f32 v0, v0, 0x3a000000, v240
	v_mov_b32_e32 v151, v150
	v_or_b32_e32 v176, s8, v165
	v_rsq_f32_e32 v0, v0
	v_permlane16_swap_b32_e32 v150, v151
	v_ashrrev_i32_e32 v177, 31, v176
	v_add_f32_e32 v154, v150, v151
	v_add_u32_e32 v150, s3, v156
	v_lshl_add_u64 v[152:153], v[176:177], 1, v[152:153]
	s_movk_i32 s3, 0x1800
	v_mad_i64_i32 v[180:181], s[8:9], v150, s3, v[152:153]
	s_and_b32 s3, s2, -4
	v_mov_b32_e32 v174, v173
	v_mov_b32_e32 v172, v171
	v_mov_b32_e32 v170, v169
	v_mov_b32_e32 v168, v161
	v_mov_b32_e32 v160, v159
	v_mov_b32_e32 v158, v157
	v_mov_b32_e32 v155, v154
	s_cmp_eq_u32 s3, 4
	v_permlane32_swap_b32_e32 v173, v174
	v_permlane32_swap_b32_e32 v171, v172
	v_permlane32_swap_b32_e32 v169, v170
	v_permlane32_swap_b32_e32 v161, v168
	v_permlane32_swap_b32_e32 v159, v160
	v_permlane32_swap_b32_e32 v157, v158
	v_permlane32_swap_b32_e32 v154, v155
	v_ashrrev_i32_e32 v151, 31, v150
	v_pk_mul_f32 v[128:129], v[128:129], v[0:1] op_sel_hi:[1,0]
	v_pk_mul_f32 v[126:127], v[126:127], v[0:1] op_sel_hi:[1,0]
	v_pk_mul_f32 v[124:125], v[124:125], v[0:1] op_sel_hi:[1,0]
	v_pk_mul_f32 v[122:123], v[122:123], v[0:1] op_sel_hi:[1,0]
	v_cvt_pk_bf16_f32 v176, v126, v127
	v_cvt_pk_bf16_f32 v177, v128, v129
	v_pk_mul_f32 v[120:121], v[120:121], v[0:1] op_sel_hi:[1,0]
	v_cvt_pk_bf16_f32 v178, v122, v123
	v_cvt_pk_bf16_f32 v179, v124, v125
	v_pk_mul_f32 v[118:119], v[118:119], v[0:1] op_sel_hi:[1,0]
	v_pk_mul_f32 v[116:117], v[116:117], v[0:1] op_sel_hi:[1,0]
	v_pk_mul_f32 v[114:115], v[114:115], v[0:1] op_sel_hi:[1,0]
	s_cselect_b64 s[16:17], -1, 0
	s_cmp_lg_u32 s3, 4
	ds_bpermute_b32 v206, v255, v176
	ds_bpermute_b32 v207, v255, v177
	ds_bpermute_b32 v208, v255, v178
	ds_bpermute_b32 v209, v255, v179
	s_nop 1
	v_cvt_pk_bf16_f32 v176, v118, v119
	v_cvt_pk_bf16_f32 v177, v120, v121
	v_cvt_pk_bf16_f32 v178, v114, v115
	v_cvt_pk_bf16_f32 v179, v116, v117
	ds_bpermute_b32 v176, v255, v176
	ds_bpermute_b32 v177, v255, v177
	ds_bpermute_b32 v178, v255, v178
	ds_bpermute_b32 v179, v255, v179
	v_lshl_add_u64 v[180:181], v[180:181], 0, v[252:253]
	s_waitcnt lgkmcnt(4)
	global_store_dwordx4 v[180:181], v[206:209], off
	s_waitcnt lgkmcnt(0)
	global_store_dwordx4 v[180:181], v[176:179], off offset:256
	s_cbranch_scc1 .LBB0_514
	v_mul_f32_e32 v0, v127, v127
	v_mul_f32_e32 v123, v123, v123
	v_mul_f32_e32 v119, v119, v119
	v_mul_f32_e32 v115, v115, v115
	v_fmac_f32_e32 v0, v126, v126
	v_mul_f32_e32 v126, v129, v129
	v_fmac_f32_e32 v123, v122, v122
	v_mul_f32_e32 v122, v125, v125
	v_fmac_f32_e32 v119, v118, v118
	v_mul_f32_e32 v118, v121, v121
	v_fmac_f32_e32 v115, v114, v114
	v_mul_f32_e32 v114, v117, v117
	v_fmac_f32_e32 v126, v128, v128
	v_fmac_f32_e32 v122, v124, v124
	v_fmac_f32_e32 v118, v120, v120
	v_fmac_f32_e32 v114, v116, v116
	v_add_f32_e32 v0, v0, v126
	v_add_f32_e32 v122, v123, v122
	v_add_f32_e32 v118, v119, v118
	v_add_f32_e32 v114, v115, v114
	v_add_f32_e32 v0, v0, v122
	v_add_f32_e32 v115, v118, v114
	v_mov_b32_e32 v114, v0
	v_mov_b32_e32 v116, v115
	s_nop 0
	v_permlane16_swap_b32_e32 v0, v114
	v_permlane16_swap_b32_e32 v115, v116
	v_add_f32_e32 v0, v0, v114
	v_add_f32_e32 v115, v115, v116
	v_mov_b32_e32 v114, v0
	v_mov_b32_e32 v116, v115
	s_nop 0
	v_permlane32_swap_b32_e32 v0, v114
	v_permlane32_swap_b32_e32 v115, v116
	s_and_saveexec_b64 s[8:9], s[4:5]
	s_cbranch_execz .LBB0_513
	v_add_f32_e32 v116, v115, v116
	v_add_f32_e32 v0, v0, v114
	v_lshlrev_b64 v[114:115], 7, v[150:151]
	v_lshl_add_u64 v[114:115], v[138:139], 0, v[114:115]
	s_lshl_b32 s36, s2, 3
	s_mov_b32 s37, s40
	v_lshl_add_u64 v[114:115], s[36:37], 2, v[114:115]
	s_lshl_b32 s36, s27, 2
	v_lshl_add_u64 v[114:115], v[114:115], 0, s[36:37]
	global_store_dword v[114:115], v0, off offset:-128
	global_store_dword v[114:115], v116, off offset:-112

.LBB0_514:
	v_add_f32_e32 v0, v173, v174
	v_fmamk_f32 v0, v0, 0x3a000000, v240
	v_rsq_f32_e32 v0, v0
	v_or_b32_e32 v114, 16, v150
	s_movk_i32 s3, 0x1800
	v_mad_i64_i32 v[120:121], s[8:9], v114, s3, v[152:153]
	v_pk_mul_f32 v[112:113], v[112:113], v[0:1] op_sel_hi:[1,0]
	v_pk_mul_f32 v[110:111], v[110:111], v[0:1] op_sel_hi:[1,0]
	v_pk_mul_f32 v[108:109], v[108:109], v[0:1] op_sel_hi:[1,0]
	v_pk_mul_f32 v[106:107], v[106:107], v[0:1] op_sel_hi:[1,0]
	v_pk_mul_f32 v[104:105], v[104:105], v[0:1] op_sel_hi:[1,0]
	v_pk_mul_f32 v[102:103], v[102:103], v[0:1] op_sel_hi:[1,0]
	v_pk_mul_f32 v[100:101], v[100:101], v[0:1] op_sel_hi:[1,0]
	v_pk_mul_f32 v[98:99], v[98:99], v[0:1] op_sel_hi:[1,0]
	v_cndmask_b32_e64 v0, 0, 1, s[16:17]
	v_cvt_pk_bf16_f32 v116, v110, v111
	v_cvt_pk_bf16_f32 v117, v112, v113
	v_cvt_pk_bf16_f32 v118, v106, v107
	v_cvt_pk_bf16_f32 v119, v108, v109
	v_cmp_ne_u32_e64 s[8:9], 1, v0
	s_andn2_b64 vcc, exec, s[16:17]
	ds_bpermute_b32 v206, v255, v116
	ds_bpermute_b32 v207, v255, v117
	ds_bpermute_b32 v208, v255, v118
	ds_bpermute_b32 v209, v255, v119
	s_nop 1
	v_cvt_pk_bf16_f32 v116, v102, v103
	v_cvt_pk_bf16_f32 v117, v104, v105
	v_cvt_pk_bf16_f32 v118, v98, v99
	v_cvt_pk_bf16_f32 v119, v100, v101
	ds_bpermute_b32 v116, v255, v116
	ds_bpermute_b32 v117, v255, v117
	ds_bpermute_b32 v118, v255, v118
	ds_bpermute_b32 v119, v255, v119
	v_lshl_add_u64 v[120:121], v[120:121], 0, v[252:253]
	s_waitcnt lgkmcnt(4)
	global_store_dwordx4 v[120:121], v[206:209], off
	s_waitcnt lgkmcnt(0)
	global_store_dwordx4 v[120:121], v[116:119], off offset:256
	s_cbranch_vccnz .LBB0_518
	v_mul_f32_e32 v0, v111, v111
	v_mul_f32_e32 v107, v107, v107
	v_mul_f32_e32 v103, v103, v103
	v_mul_f32_e32 v99, v99, v99
	v_fmac_f32_e32 v0, v110, v110
	v_mul_f32_e32 v110, v113, v113
	v_fmac_f32_e32 v107, v106, v106
	v_mul_f32_e32 v106, v109, v109
	v_fmac_f32_e32 v103, v102, v102
	v_mul_f32_e32 v102, v105, v105
	v_fmac_f32_e32 v99, v98, v98
	v_mul_f32_e32 v98, v101, v101
	v_fmac_f32_e32 v110, v112, v112
	v_fmac_f32_e32 v106, v108, v108
	v_fmac_f32_e32 v102, v104, v104
	v_fmac_f32_e32 v98, v100, v100
	v_add_f32_e32 v0, v0, v110
	v_add_f32_e32 v106, v107, v106
	v_add_f32_e32 v102, v103, v102
	v_add_f32_e32 v98, v99, v98
	v_add_f32_e32 v0, v0, v106
	v_add_f32_e32 v99, v102, v98
	v_mov_b32_e32 v98, v0
	v_mov_b32_e32 v100, v99
	s_nop 0
	v_permlane16_swap_b32_e32 v0, v98
	v_permlane16_swap_b32_e32 v99, v100
	v_add_f32_e32 v0, v0, v98
	v_add_f32_e32 v99, v99, v100
	v_mov_b32_e32 v98, v0
	v_mov_b32_e32 v100, v99
	s_nop 0
	v_permlane32_swap_b32_e32 v0, v98
	v_permlane32_swap_b32_e32 v99, v100
	s_and_saveexec_b64 s[16:17], s[4:5]
	s_cbranch_execz .LBB0_517
	v_ashrrev_i32_e32 v115, 31, v114
	v_add_f32_e32 v100, v99, v100
	v_add_f32_e32 v0, v0, v98
	v_lshlrev_b64 v[98:99], 7, v[114:115]
	v_lshl_add_u64 v[98:99], v[138:139], 0, v[98:99]
	s_lshl_b32 s36, s2, 3
	s_mov_b32 s37, s40
	v_lshl_add_u64 v[98:99], s[36:37], 2, v[98:99]
	s_lshl_b32 s36, s27, 2
	v_lshl_add_u64 v[98:99], v[98:99], 0, s[36:37]
	global_store_dword v[98:99], v0, off offset:-128
	global_store_dword v[98:99], v100, off offset:-112

.LBB0_518:
	v_add_f32_e32 v0, v171, v172
	v_fmamk_f32 v0, v0, 0x3a000000, v240
	v_rsq_f32_e32 v0, v0
	v_or_b32_e32 v98, 32, v150
	v_mad_i64_i32 v[104:105], s[16:17], v98, s3, v[152:153]
	v_pk_mul_f32 v[96:97], v[96:97], v[0:1] op_sel_hi:[1,0]
	v_pk_mul_f32 v[94:95], v[94:95], v[0:1] op_sel_hi:[1,0]
	v_pk_mul_f32 v[92:93], v[92:93], v[0:1] op_sel_hi:[1,0]
	v_pk_mul_f32 v[90:91], v[90:91], v[0:1] op_sel_hi:[1,0]
	v_cvt_pk_bf16_f32 v100, v94, v95
	v_cvt_pk_bf16_f32 v101, v96, v97
	v_pk_mul_f32 v[88:89], v[88:89], v[0:1] op_sel_hi:[1,0]
	v_cvt_pk_bf16_f32 v102, v90, v91
	v_cvt_pk_bf16_f32 v103, v92, v93
	v_pk_mul_f32 v[86:87], v[86:87], v[0:1] op_sel_hi:[1,0]
	v_pk_mul_f32 v[84:85], v[84:85], v[0:1] op_sel_hi:[1,0]
	v_pk_mul_f32 v[82:83], v[82:83], v[0:1] op_sel_hi:[1,0]
	s_and_b64 vcc, exec, s[8:9]
	ds_bpermute_b32 v206, v255, v100
	ds_bpermute_b32 v207, v255, v101
	ds_bpermute_b32 v208, v255, v102
	ds_bpermute_b32 v209, v255, v103
	s_nop 1
	v_cvt_pk_bf16_f32 v100, v86, v87
	v_cvt_pk_bf16_f32 v101, v88, v89
	v_cvt_pk_bf16_f32 v102, v82, v83
	v_cvt_pk_bf16_f32 v103, v84, v85
	ds_bpermute_b32 v100, v255, v100
	ds_bpermute_b32 v101, v255, v101
	ds_bpermute_b32 v102, v255, v102
	ds_bpermute_b32 v103, v255, v103
	v_lshl_add_u64 v[104:105], v[104:105], 0, v[252:253]
	s_waitcnt lgkmcnt(4)
	global_store_dwordx4 v[104:105], v[206:209], off
	s_waitcnt lgkmcnt(0)
	global_store_dwordx4 v[104:105], v[100:103], off offset:256
	s_cbranch_vccnz .LBB0_522
	v_mul_f32_e32 v0, v95, v95
	v_mul_f32_e32 v91, v91, v91
	v_mul_f32_e32 v87, v87, v87
	v_mul_f32_e32 v83, v83, v83
	v_fmac_f32_e32 v0, v94, v94
	v_mul_f32_e32 v94, v97, v97
	v_fmac_f32_e32 v91, v90, v90
	v_mul_f32_e32 v90, v93, v93
	v_fmac_f32_e32 v87, v86, v86
	v_mul_f32_e32 v86, v89, v89
	v_fmac_f32_e32 v83, v82, v82
	v_mul_f32_e32 v82, v85, v85
	v_fmac_f32_e32 v94, v96, v96
	v_fmac_f32_e32 v90, v92, v92
	v_fmac_f32_e32 v86, v88, v88
	v_fmac_f32_e32 v82, v84, v84
	v_add_f32_e32 v0, v0, v94
	v_add_f32_e32 v90, v91, v90
	v_add_f32_e32 v86, v87, v86
	v_add_f32_e32 v82, v83, v82
	v_add_f32_e32 v0, v0, v90
	v_add_f32_e32 v83, v86, v82
	v_mov_b32_e32 v82, v0
	v_mov_b32_e32 v84, v83
	s_nop 0
	v_permlane16_swap_b32_e32 v0, v82
	v_permlane16_swap_b32_e32 v83, v84
	v_add_f32_e32 v0, v0, v82
	v_add_f32_e32 v83, v83, v84
	v_mov_b32_e32 v82, v0
	v_mov_b32_e32 v84, v83
	s_nop 0
	v_permlane32_swap_b32_e32 v0, v82
	v_permlane32_swap_b32_e32 v83, v84
	s_and_saveexec_b64 s[16:17], s[4:5]
	s_cbranch_execz .LBB0_521
	v_ashrrev_i32_e32 v99, 31, v98
	v_add_f32_e32 v84, v83, v84
	v_add_f32_e32 v0, v0, v82
	v_lshlrev_b64 v[82:83], 7, v[98:99]
	v_lshl_add_u64 v[82:83], v[138:139], 0, v[82:83]
	s_lshl_b32 s36, s2, 3
	s_mov_b32 s37, s40
	v_lshl_add_u64 v[82:83], s[36:37], 2, v[82:83]
	s_lshl_b32 s36, s27, 2
	v_lshl_add_u64 v[82:83], v[82:83], 0, s[36:37]
	global_store_dword v[82:83], v0, off offset:-128
	global_store_dword v[82:83], v84, off offset:-112

.LBB0_522:
	v_add_f32_e32 v0, v169, v170
	v_fmamk_f32 v0, v0, 0x3a000000, v240
	v_rsq_f32_e32 v0, v0
	v_or_b32_e32 v82, 48, v150
	v_mad_i64_i32 v[88:89], s[16:17], v82, s3, v[152:153]
	v_pk_mul_f32 v[80:81], v[80:81], v[0:1] op_sel_hi:[1,0]
	v_pk_mul_f32 v[78:79], v[78:79], v[0:1] op_sel_hi:[1,0]
	v_pk_mul_f32 v[76:77], v[76:77], v[0:1] op_sel_hi:[1,0]
	v_pk_mul_f32 v[74:75], v[74:75], v[0:1] op_sel_hi:[1,0]
	v_cvt_pk_bf16_f32 v84, v78, v79
	v_cvt_pk_bf16_f32 v85, v80, v81
	v_pk_mul_f32 v[72:73], v[72:73], v[0:1] op_sel_hi:[1,0]
	v_cvt_pk_bf16_f32 v86, v74, v75
	v_cvt_pk_bf16_f32 v87, v76, v77
	v_pk_mul_f32 v[70:71], v[70:71], v[0:1] op_sel_hi:[1,0]
	v_pk_mul_f32 v[68:69], v[68:69], v[0:1] op_sel_hi:[1,0]
	v_pk_mul_f32 v[66:67], v[66:67], v[0:1] op_sel_hi:[1,0]
	s_and_b64 vcc, exec, s[8:9]
	ds_bpermute_b32 v206, v255, v84
	ds_bpermute_b32 v207, v255, v85
	ds_bpermute_b32 v208, v255, v86
	ds_bpermute_b32 v209, v255, v87
	s_nop 1
	v_cvt_pk_bf16_f32 v84, v70, v71
	v_cvt_pk_bf16_f32 v85, v72, v73
	v_cvt_pk_bf16_f32 v86, v66, v67
	v_cvt_pk_bf16_f32 v87, v68, v69
	ds_bpermute_b32 v84, v255, v84
	ds_bpermute_b32 v85, v255, v85
	ds_bpermute_b32 v86, v255, v86
	ds_bpermute_b32 v87, v255, v87
	v_lshl_add_u64 v[88:89], v[88:89], 0, v[252:253]
	s_waitcnt lgkmcnt(4)
	global_store_dwordx4 v[88:89], v[206:209], off
	s_waitcnt lgkmcnt(0)
	global_store_dwordx4 v[88:89], v[84:87], off offset:256
	s_cbranch_vccnz .LBB0_526
	v_mul_f32_e32 v0, v79, v79
	v_mul_f32_e32 v75, v75, v75
	v_mul_f32_e32 v71, v71, v71
	v_mul_f32_e32 v67, v67, v67
	v_fmac_f32_e32 v0, v78, v78
	v_mul_f32_e32 v78, v81, v81
	v_fmac_f32_e32 v75, v74, v74
	v_mul_f32_e32 v74, v77, v77
	v_fmac_f32_e32 v71, v70, v70
	v_mul_f32_e32 v70, v73, v73
	v_fmac_f32_e32 v67, v66, v66
	v_mul_f32_e32 v66, v69, v69
	v_fmac_f32_e32 v78, v80, v80
	v_fmac_f32_e32 v74, v76, v76
	v_fmac_f32_e32 v70, v72, v72
	v_fmac_f32_e32 v66, v68, v68
	v_add_f32_e32 v0, v0, v78
	v_add_f32_e32 v74, v75, v74
	v_add_f32_e32 v70, v71, v70
	v_add_f32_e32 v66, v67, v66
	v_add_f32_e32 v0, v0, v74
	v_add_f32_e32 v67, v70, v66
	v_mov_b32_e32 v66, v0
	v_mov_b32_e32 v68, v67
	s_nop 0
	v_permlane16_swap_b32_e32 v0, v66
	v_permlane16_swap_b32_e32 v67, v68
	v_add_f32_e32 v0, v0, v66
	v_add_f32_e32 v67, v67, v68
	v_mov_b32_e32 v66, v0
	v_mov_b32_e32 v68, v67
	s_nop 0
	v_permlane32_swap_b32_e32 v0, v66
	v_permlane32_swap_b32_e32 v67, v68
	s_and_saveexec_b64 s[16:17], s[4:5]
	s_cbranch_execz .LBB0_525
	v_ashrrev_i32_e32 v83, 31, v82
	v_add_f32_e32 v68, v67, v68
	v_add_f32_e32 v0, v0, v66
	v_lshlrev_b64 v[66:67], 7, v[82:83]
	v_lshl_add_u64 v[66:67], v[138:139], 0, v[66:67]
	s_lshl_b32 s36, s2, 3
	s_mov_b32 s37, s40
	v_lshl_add_u64 v[66:67], s[36:37], 2, v[66:67]
	s_lshl_b32 s36, s27, 2
	v_lshl_add_u64 v[66:67], v[66:67], 0, s[36:37]
	global_store_dword v[66:67], v0, off offset:-128
	global_store_dword v[66:67], v68, off offset:-112

.LBB0_526:
	v_add_f32_e32 v0, v161, v168
	v_fmamk_f32 v0, v0, 0x3a000000, v240
	v_rsq_f32_e32 v0, v0
	v_add_u32_e32 v66, 0x80, v150
	v_mad_i64_i32 v[72:73], s[16:17], v66, s3, v[152:153]
	v_pk_mul_f32 v[64:65], v[64:65], v[0:1] op_sel_hi:[1,0]
	v_pk_mul_f32 v[62:63], v[62:63], v[0:1] op_sel_hi:[1,0]
	v_pk_mul_f32 v[60:61], v[60:61], v[0:1] op_sel_hi:[1,0]
	v_pk_mul_f32 v[58:59], v[58:59], v[0:1] op_sel_hi:[1,0]
	v_cvt_pk_bf16_f32 v68, v62, v63
	v_cvt_pk_bf16_f32 v69, v64, v65
	v_pk_mul_f32 v[56:57], v[56:57], v[0:1] op_sel_hi:[1,0]
	v_cvt_pk_bf16_f32 v70, v58, v59
	v_cvt_pk_bf16_f32 v71, v60, v61
	v_pk_mul_f32 v[54:55], v[54:55], v[0:1] op_sel_hi:[1,0]
	v_pk_mul_f32 v[52:53], v[52:53], v[0:1] op_sel_hi:[1,0]
	v_pk_mul_f32 v[50:51], v[50:51], v[0:1] op_sel_hi:[1,0]
	s_and_b64 vcc, exec, s[8:9]
	ds_bpermute_b32 v206, v255, v68
	ds_bpermute_b32 v207, v255, v69
	ds_bpermute_b32 v208, v255, v70
	ds_bpermute_b32 v209, v255, v71
	s_nop 1
	v_cvt_pk_bf16_f32 v68, v54, v55
	v_cvt_pk_bf16_f32 v69, v56, v57
	v_cvt_pk_bf16_f32 v70, v50, v51
	v_cvt_pk_bf16_f32 v71, v52, v53
	ds_bpermute_b32 v68, v255, v68
	ds_bpermute_b32 v69, v255, v69
	ds_bpermute_b32 v70, v255, v70
	ds_bpermute_b32 v71, v255, v71
	v_lshl_add_u64 v[72:73], v[72:73], 0, v[252:253]
	s_waitcnt lgkmcnt(4)
	global_store_dwordx4 v[72:73], v[206:209], off
	s_waitcnt lgkmcnt(0)
	global_store_dwordx4 v[72:73], v[68:71], off offset:256
	s_cbranch_vccnz .LBB0_530
	v_mul_f32_e32 v0, v63, v63
	v_mul_f32_e32 v59, v59, v59
	v_mul_f32_e32 v55, v55, v55
	v_mul_f32_e32 v51, v51, v51
	v_fmac_f32_e32 v0, v62, v62
	v_mul_f32_e32 v62, v65, v65
	v_fmac_f32_e32 v59, v58, v58
	v_mul_f32_e32 v58, v61, v61
	v_fmac_f32_e32 v55, v54, v54
	v_mul_f32_e32 v54, v57, v57
	v_fmac_f32_e32 v51, v50, v50
	v_mul_f32_e32 v50, v53, v53
	v_fmac_f32_e32 v62, v64, v64
	v_fmac_f32_e32 v58, v60, v60
	v_fmac_f32_e32 v54, v56, v56
	v_fmac_f32_e32 v50, v52, v52
	v_add_f32_e32 v0, v0, v62
	v_add_f32_e32 v58, v59, v58
	v_add_f32_e32 v54, v55, v54
	v_add_f32_e32 v50, v51, v50
	v_add_f32_e32 v0, v0, v58
	v_add_f32_e32 v51, v54, v50
	v_mov_b32_e32 v50, v0
	v_mov_b32_e32 v52, v51
	s_nop 0
	v_permlane16_swap_b32_e32 v0, v50
	v_permlane16_swap_b32_e32 v51, v52
	v_add_f32_e32 v0, v0, v50
	v_add_f32_e32 v51, v51, v52
	v_mov_b32_e32 v50, v0
	v_mov_b32_e32 v52, v51
	s_nop 0
	v_permlane32_swap_b32_e32 v0, v50
	v_permlane32_swap_b32_e32 v51, v52
	s_and_saveexec_b64 s[16:17], s[4:5]
	s_cbranch_execz .LBB0_529
	v_ashrrev_i32_e32 v67, 31, v66
	v_add_f32_e32 v52, v51, v52
	v_add_f32_e32 v0, v0, v50
	v_lshlrev_b64 v[50:51], 7, v[66:67]
	v_lshl_add_u64 v[50:51], v[138:139], 0, v[50:51]
	s_lshl_b32 s36, s2, 3
	s_mov_b32 s37, s40
	v_lshl_add_u64 v[50:51], s[36:37], 2, v[50:51]
	s_lshl_b32 s36, s27, 2
	v_lshl_add_u64 v[50:51], v[50:51], 0, s[36:37]
	global_store_dword v[50:51], v0, off offset:-128
	global_store_dword v[50:51], v52, off offset:-112

.LBB0_530:
	v_add_f32_e32 v0, v159, v160
	v_fmamk_f32 v0, v0, 0x3a000000, v240
	v_rsq_f32_e32 v0, v0
	v_add_u32_e32 v50, 0x90, v150
	v_mad_i64_i32 v[56:57], s[16:17], v50, s3, v[152:153]
	v_pk_mul_f32 v[48:49], v[48:49], v[0:1] op_sel_hi:[1,0]
	v_pk_mul_f32 v[46:47], v[46:47], v[0:1] op_sel_hi:[1,0]
	v_pk_mul_f32 v[44:45], v[44:45], v[0:1] op_sel_hi:[1,0]
	v_pk_mul_f32 v[42:43], v[42:43], v[0:1] op_sel_hi:[1,0]
	v_cvt_pk_bf16_f32 v52, v46, v47
	v_cvt_pk_bf16_f32 v53, v48, v49
	v_pk_mul_f32 v[40:41], v[40:41], v[0:1] op_sel_hi:[1,0]
	v_cvt_pk_bf16_f32 v54, v42, v43
	v_cvt_pk_bf16_f32 v55, v44, v45
	v_pk_mul_f32 v[38:39], v[38:39], v[0:1] op_sel_hi:[1,0]
	v_pk_mul_f32 v[36:37], v[36:37], v[0:1] op_sel_hi:[1,0]
	v_pk_mul_f32 v[34:35], v[34:35], v[0:1] op_sel_hi:[1,0]
	s_and_b64 vcc, exec, s[8:9]
	ds_bpermute_b32 v206, v255, v52
	ds_bpermute_b32 v207, v255, v53
	ds_bpermute_b32 v208, v255, v54
	ds_bpermute_b32 v209, v255, v55
	s_nop 1
	v_cvt_pk_bf16_f32 v52, v38, v39
	v_cvt_pk_bf16_f32 v53, v40, v41
	v_cvt_pk_bf16_f32 v54, v34, v35
	v_cvt_pk_bf16_f32 v55, v36, v37
	ds_bpermute_b32 v52, v255, v52
	ds_bpermute_b32 v53, v255, v53
	ds_bpermute_b32 v54, v255, v54
	ds_bpermute_b32 v55, v255, v55
	v_lshl_add_u64 v[56:57], v[56:57], 0, v[252:253]
	s_waitcnt lgkmcnt(4)
	global_store_dwordx4 v[56:57], v[206:209], off
	s_waitcnt lgkmcnt(0)
	global_store_dwordx4 v[56:57], v[52:55], off offset:256
	s_cbranch_vccnz .LBB0_534
	v_mul_f32_e32 v0, v47, v47
	v_mul_f32_e32 v43, v43, v43
	v_mul_f32_e32 v39, v39, v39
	v_mul_f32_e32 v35, v35, v35
	v_fmac_f32_e32 v0, v46, v46
	v_mul_f32_e32 v46, v49, v49
	v_fmac_f32_e32 v43, v42, v42
	v_mul_f32_e32 v42, v45, v45
	v_fmac_f32_e32 v39, v38, v38
	v_mul_f32_e32 v38, v41, v41
	v_fmac_f32_e32 v35, v34, v34
	v_mul_f32_e32 v34, v37, v37
	v_fmac_f32_e32 v46, v48, v48
	v_fmac_f32_e32 v42, v44, v44
	v_fmac_f32_e32 v38, v40, v40
	v_fmac_f32_e32 v34, v36, v36
	v_add_f32_e32 v0, v0, v46
	v_add_f32_e32 v42, v43, v42
	v_add_f32_e32 v38, v39, v38
	v_add_f32_e32 v34, v35, v34
	v_add_f32_e32 v0, v0, v42
	v_add_f32_e32 v35, v38, v34
	v_mov_b32_e32 v34, v0
	v_mov_b32_e32 v36, v35
	s_nop 0
	v_permlane16_swap_b32_e32 v0, v34
	v_permlane16_swap_b32_e32 v35, v36
	v_add_f32_e32 v0, v0, v34
	v_add_f32_e32 v35, v35, v36
	v_mov_b32_e32 v34, v0
	v_mov_b32_e32 v36, v35
	s_nop 0
	v_permlane32_swap_b32_e32 v0, v34
	v_permlane32_swap_b32_e32 v35, v36
	s_and_saveexec_b64 s[16:17], s[4:5]
	s_cbranch_execz .LBB0_533
	v_ashrrev_i32_e32 v51, 31, v50
	v_add_f32_e32 v36, v35, v36
	v_add_f32_e32 v0, v0, v34
	v_lshlrev_b64 v[34:35], 7, v[50:51]
	v_lshl_add_u64 v[34:35], v[138:139], 0, v[34:35]
	s_lshl_b32 s36, s2, 3
	s_mov_b32 s37, s40
	v_lshl_add_u64 v[34:35], s[36:37], 2, v[34:35]
	s_lshl_b32 s36, s27, 2
	v_lshl_add_u64 v[34:35], v[34:35], 0, s[36:37]
	global_store_dword v[34:35], v0, off offset:-128
	global_store_dword v[34:35], v36, off offset:-112

.LBB0_534:
	v_add_f32_e32 v0, v157, v158
	v_fmamk_f32 v0, v0, 0x3a000000, v240
	v_rsq_f32_e32 v0, v0
	v_add_u32_e32 v34, 0xa0, v150
	v_mad_i64_i32 v[40:41], s[16:17], v34, s3, v[152:153]
	v_pk_mul_f32 v[32:33], v[32:33], v[0:1] op_sel_hi:[1,0]
	v_pk_mul_f32 v[30:31], v[30:31], v[0:1] op_sel_hi:[1,0]
	v_pk_mul_f32 v[28:29], v[28:29], v[0:1] op_sel_hi:[1,0]
	v_pk_mul_f32 v[26:27], v[26:27], v[0:1] op_sel_hi:[1,0]
	v_cvt_pk_bf16_f32 v36, v30, v31
	v_cvt_pk_bf16_f32 v37, v32, v33
	v_pk_mul_f32 v[24:25], v[24:25], v[0:1] op_sel_hi:[1,0]
	v_cvt_pk_bf16_f32 v38, v26, v27
	v_cvt_pk_bf16_f32 v39, v28, v29
	v_pk_mul_f32 v[22:23], v[22:23], v[0:1] op_sel_hi:[1,0]
	v_pk_mul_f32 v[20:21], v[20:21], v[0:1] op_sel_hi:[1,0]
	v_pk_mul_f32 v[18:19], v[18:19], v[0:1] op_sel_hi:[1,0]
	s_and_b64 vcc, exec, s[8:9]
	ds_bpermute_b32 v206, v255, v36
	ds_bpermute_b32 v207, v255, v37
	ds_bpermute_b32 v208, v255, v38
	ds_bpermute_b32 v209, v255, v39
	s_nop 1
	v_cvt_pk_bf16_f32 v36, v22, v23
	v_cvt_pk_bf16_f32 v37, v24, v25
	v_cvt_pk_bf16_f32 v38, v18, v19
	v_cvt_pk_bf16_f32 v39, v20, v21
	ds_bpermute_b32 v36, v255, v36
	ds_bpermute_b32 v37, v255, v37
	ds_bpermute_b32 v38, v255, v38
	ds_bpermute_b32 v39, v255, v39
	v_lshl_add_u64 v[40:41], v[40:41], 0, v[252:253]
	s_waitcnt lgkmcnt(4)
	global_store_dwordx4 v[40:41], v[206:209], off
	s_waitcnt lgkmcnt(0)
	global_store_dwordx4 v[40:41], v[36:39], off offset:256
	s_cbranch_vccnz .LBB0_538
	v_mul_f32_e32 v0, v31, v31
	v_mul_f32_e32 v27, v27, v27
	v_mul_f32_e32 v23, v23, v23
	v_mul_f32_e32 v19, v19, v19
	v_fmac_f32_e32 v0, v30, v30
	v_mul_f32_e32 v30, v33, v33
	v_fmac_f32_e32 v27, v26, v26
	v_mul_f32_e32 v26, v29, v29
	v_fmac_f32_e32 v23, v22, v22
	v_mul_f32_e32 v22, v25, v25
	v_fmac_f32_e32 v19, v18, v18
	v_mul_f32_e32 v18, v21, v21
	v_fmac_f32_e32 v30, v32, v32
	v_fmac_f32_e32 v26, v28, v28
	v_fmac_f32_e32 v22, v24, v24
	v_fmac_f32_e32 v18, v20, v20
	v_add_f32_e32 v0, v0, v30
	v_add_f32_e32 v26, v27, v26
	v_add_f32_e32 v22, v23, v22
	v_add_f32_e32 v18, v19, v18
	v_add_f32_e32 v0, v0, v26
	v_add_f32_e32 v19, v22, v18
	v_mov_b32_e32 v18, v0
	v_mov_b32_e32 v20, v19
	s_nop 0
	v_permlane16_swap_b32_e32 v0, v18
	v_permlane16_swap_b32_e32 v19, v20
	v_add_f32_e32 v0, v0, v18
	v_add_f32_e32 v19, v19, v20
	v_mov_b32_e32 v18, v0
	v_mov_b32_e32 v20, v19
	s_nop 0
	v_permlane32_swap_b32_e32 v0, v18
	v_permlane32_swap_b32_e32 v19, v20
	s_and_saveexec_b64 s[16:17], s[4:5]
	s_cbranch_execz .LBB0_537
	v_ashrrev_i32_e32 v35, 31, v34
	v_add_f32_e32 v20, v19, v20
	v_add_f32_e32 v0, v0, v18
	v_lshlrev_b64 v[18:19], 7, v[34:35]
	v_lshl_add_u64 v[18:19], v[138:139], 0, v[18:19]
	s_lshl_b32 s36, s2, 3
	s_mov_b32 s37, s40
	v_lshl_add_u64 v[18:19], s[36:37], 2, v[18:19]
	s_lshl_b32 s36, s27, 2
	v_lshl_add_u64 v[18:19], v[18:19], 0, s[36:37]
	global_store_dword v[18:19], v0, off offset:-128
	global_store_dword v[18:19], v20, off offset:-112

.LBB0_538:
	v_add_f32_e32 v0, v154, v155
	v_fmamk_f32 v0, v0, 0x3a000000, v240
	v_rsq_f32_e32 v0, v0
	v_add_u32_e32 v18, 0xb0, v150
	v_mad_i64_i32 v[26:27], s[16:17], v18, s3, v[152:153]
	v_pk_mul_f32 v[12:13], v[12:13], v[0:1] op_sel_hi:[1,0]
	v_pk_mul_f32 v[10:11], v[10:11], v[0:1] op_sel_hi:[1,0]
	v_pk_mul_f32 v[8:9], v[8:9], v[0:1] op_sel_hi:[1,0]
	v_cvt_pk_bf16_f32 v20, v10, v11
	v_cvt_pk_bf16_f32 v21, v12, v13
	v_pk_mul_f32 v[6:7], v[6:7], v[0:1] op_sel_hi:[1,0]
	v_pk_mul_f32 v[4:5], v[4:5], v[0:1] op_sel_hi:[1,0]
	v_cvt_pk_bf16_f32 v22, v6, v7
	v_cvt_pk_bf16_f32 v23, v8, v9
	ds_bpermute_b32 v206, v255, v20
	ds_bpermute_b32 v207, v255, v21
	ds_bpermute_b32 v208, v255, v22
	ds_bpermute_b32 v209, v255, v23
	v_pk_mul_f32 v[14:15], v[14:15], v[0:1] op_sel_hi:[1,0]
	s_and_b64 vcc, exec, s[8:9]
	v_pk_mul_f32 v[20:21], v[2:3], v[0:1] op_sel_hi:[1,0]
	v_pk_mul_f32 v[2:3], v[16:17], v[0:1] op_sel_hi:[1,0]
	v_cvt_pk_bf16_f32 v22, v20, v21
	v_cvt_pk_bf16_f32 v23, v4, v5
	v_cvt_pk_bf16_f32 v24, v14, v15
	s_nop 0
	v_cvt_pk_bf16_f32 v25, v2, v3
	ds_bpermute_b32 v22, v255, v22
	ds_bpermute_b32 v23, v255, v23
	ds_bpermute_b32 v24, v255, v24
	ds_bpermute_b32 v25, v255, v25
	v_lshl_add_u64 v[26:27], v[26:27], 0, v[252:253]
	s_waitcnt lgkmcnt(4)
	global_store_dwordx4 v[26:27], v[206:209], off
	s_waitcnt lgkmcnt(0)
	global_store_dwordx4 v[26:27], v[22:25], off offset:256
	s_cbranch_vccnz .LBB0_542
	v_mul_f32_e32 v0, v11, v11
	v_mul_f32_e32 v7, v7, v7
	v_fmac_f32_e32 v0, v10, v10
	v_mul_f32_e32 v10, v13, v13
	v_fmac_f32_e32 v7, v6, v6
	v_mul_f32_e32 v6, v9, v9
	v_fmac_f32_e32 v10, v12, v12
	v_fmac_f32_e32 v6, v8, v8
	v_add_f32_e32 v0, v0, v10
	v_add_f32_e32 v6, v7, v6
	v_add_f32_e32 v0, v0, v6
	v_mul_f32_e32 v6, v21, v21
	v_mul_f32_e32 v5, v5, v5
	v_fmac_f32_e32 v6, v20, v20
	v_fmac_f32_e32 v5, v4, v4
	v_add_f32_e32 v4, v6, v5
	v_mul_f32_e32 v5, v15, v15
	v_mul_f32_e32 v3, v3, v3
	v_fmac_f32_e32 v5, v14, v14
	v_fmac_f32_e32 v3, v2, v2
	v_add_f32_e32 v2, v5, v3
	v_add_f32_e32 v3, v4, v2
	v_mov_b32_e32 v2, v0
	v_mov_b32_e32 v4, v3
	s_nop 0
	v_permlane16_swap_b32_e32 v0, v2
	v_permlane16_swap_b32_e32 v3, v4
	v_add_f32_e32 v0, v0, v2
	v_add_f32_e32 v3, v3, v4
	v_mov_b32_e32 v2, v0
	v_mov_b32_e32 v4, v3
	s_nop 0
	v_permlane32_swap_b32_e32 v0, v2
	v_permlane32_swap_b32_e32 v3, v4
	s_and_saveexec_b64 s[8:9], s[4:5]
	s_cbranch_execz .LBB0_541
	v_ashrrev_i32_e32 v19, 31, v18
	v_add_f32_e32 v4, v3, v4
	v_add_f32_e32 v0, v0, v2
	v_lshlrev_b64 v[2:3], 7, v[18:19]
	v_lshl_add_u64 v[2:3], v[138:139], 0, v[2:3]
	s_lshl_b32 s2, s2, 3
	s_mov_b32 s3, s40
	v_lshl_add_u64 v[2:3], s[2:3], 2, v[2:3]
	s_lshl_b32 s2, s27, 2
	v_lshl_add_u64 v[2:3], v[2:3], 0, s[2:3]
	global_store_dword v[2:3], v0, off offset:-128
	global_store_dword v[2:3], v4, off offset:-112
